# cand32 + in-projection GEMM epilogue: per-row 1/rms loads issued at the unit-loop head
# baseline (speedup 1.0000x reference)
.LBB0_439:
	s_lshl_b32 s98, s2, 8
	s_add_i32 s98, s98, s55
	v_add_lshl_u32 v235, s98, v153, 2
	global_load_dword v240, v235, s[14:15]
	global_load_dword v241, v235, s[14:15] offset:64
	global_load_dword v242, v235, s[14:15] offset:128
	global_load_dword v243, v235, s[14:15] offset:192
	global_load_dword v244, v235, s[14:15] offset:512
	global_load_dword v245, v235, s[14:15] offset:576
	global_load_dword v246, v235, s[14:15] offset:640
	global_load_dword v247, v235, s[14:15] offset:704
	s_add_i32 s62, s62, 1
	s_mul_i32 s0, s62, s88
	s_mul_hi_u32 s1, s62, s64
	s_add_i32 s1, s1, s0
	s_mul_i32 s0, s62, s64
	v_readlane_b32 s3, v252, 2
	s_add_u32 s46, s0, s3
	s_addc_u32 s47, s1, s89
	v_cmp_gt_i64_e32 vcc, s[46:47], v[146:147]
	v_cmp_lt_i64_e64 s[0:1], s[46:47], v[144:145]
	s_cbranch_vccnz .LBB0_445
	s_ashr_i32 s3, s46, 31
	s_lshr_b32 s3, s3, 29
	s_add_i32 s3, s46, s3
	s_and_b32 s8, s3, -8
	s_sub_i32 s8, s46, s8
	s_cmp_gt_i32 s8, -1
	s_mov_b64 s[38:39], -1
	s_cbranch_scc0 .LBB0_442
	s_lshl_b32 s44, s8, 7
	s_mov_b64 s[38:39], 0

.LBB0_449:
	s_lshl_b32 s2, s2, 8
	v_mov_b32_e32 v139, v153
	v_mov_b32_e32 v150, v157
	s_add_i32 s2, s2, s55
	v_mov_b64_e32 v[180:181], s[26:27]
	v_add_u32_e32 v176, s2, v139
	v_ashrrev_i32_e32 v177, 31, v176
	v_lshl_add_u64 v[148:149], v[176:177], 2, s[14:15]
	v_mov_b32_e32 v184, v240
	v_add_u32_e32 v174, 16, v176
	v_add_u32_e32 v170, 32, v176
	v_add_u32_e32 v166, 48, v176
	v_add_u32_e32 v162, 0x80, v176
	v_add_u32_e32 v158, 0x90, v176
	v_add_u32_e32 v154, 0xa0, v176
	v_add_u32_e32 v148, 0xb0, v176
	v_ashrrev_i32_e32 v175, 31, v174
	v_ashrrev_i32_e32 v171, 31, v170
	v_ashrrev_i32_e32 v167, 31, v166
	v_ashrrev_i32_e32 v163, 31, v162
	v_ashrrev_i32_e32 v159, 31, v158
	v_ashrrev_i32_e32 v155, 31, v154
	v_ashrrev_i32_e32 v149, 31, v148
	v_lshl_add_u64 v[186:187], v[174:175], 2, s[14:15]
	v_lshl_add_u64 v[188:189], v[170:171], 2, s[14:15]
	v_lshl_add_u64 v[190:191], v[166:167], 2, s[14:15]
	v_lshl_add_u64 v[192:193], v[162:163], 2, s[14:15]
	v_lshl_add_u64 v[194:195], v[158:159], 2, s[14:15]
	v_lshl_add_u64 v[196:197], v[154:155], 2, s[14:15]
	v_lshl_add_u64 v[198:199], v[148:149], 2, s[14:15]
	v_mov_b32_e32 v178, v241
	v_mov_b32_e32 v172, v242
	v_mov_b32_e32 v168, v243
	v_mov_b32_e32 v164, v244
	v_mov_b32_e32 v160, v245
	v_mov_b32_e32 v156, v246
	v_mov_b32_e32 v152, v247
	s_lshl_b32 s2, s6, 8
	s_and_b32 s2, s2, 0xf00
	s_or_b32 s4, s2, s56
	s_cmp_gt_i32 s6, 15
	s_cselect_b64 s[50:51], -1, 0
	v_cmp_eq_u32_e64 s[2:3], 0, v150
	v_lshl_add_u32 v150, v150, 3, s4
	s_and_b64 s[4:5], s[50:51], exec
	s_cselect_b32 s4, s61, 0x2ed00000
	s_add_u32 s4, s18, s4
	v_ashrrev_i32_e32 v151, 31, v150
	s_addc_u32 s5, s19, 0
	v_lshlrev_b64 v[182:183], 13, v[176:177]
	v_lshl_add_u64 v[150:151], v[150:151], 1, s[4:5]
	v_lshl_add_u64 v[182:183], v[150:151], 0, v[182:183]
	s_cmp_lt_i32 s6, 16
	v_pk_mul_f32 v[126:127], v[126:127], v[184:185] op_sel_hi:[1,0]
	v_pk_mul_f32 v[128:129], v[128:129], v[184:185] op_sel_hi:[1,0]
	v_pk_mul_f32 v[124:125], v[124:125], v[184:185] op_sel_hi:[1,0]
	v_pk_mul_f32 v[122:123], v[122:123], v[184:185] op_sel_hi:[1,0]
	v_pk_mul_f32 v[186:187], v[120:121], v[184:185] op_sel_hi:[1,0]
	v_pk_mul_f32 v[188:189], v[118:119], v[184:185] op_sel_hi:[1,0]
	v_pk_mul_f32 v[190:191], v[116:117], v[184:185] op_sel_hi:[1,0]
	v_pk_mul_f32 v[184:185], v[114:115], v[184:185] op_sel_hi:[1,0]
	v_and_b32_e32 v115, 0x7fffffff, v127
	v_and_b32_e32 v114, 0x7fffffff, v126
	v_pk_fma_f32 v[194:195], v[114:115], s[22:23], 1.0 op_sel_hi:[1,0,0]
	v_and_b32_e32 v121, 0x7fffffff, v129
	v_and_b32_e32 v120, 0x7fffffff, v128
	v_rcp_f32_e32 v194, v194
	v_rcp_f32_e32 v195, v195
	v_pk_fma_f32 v[196:197], v[120:121], s[22:23], 1.0 op_sel_hi:[1,0,0]
	v_pk_mul_f32 v[118:119], v[126:127], v[126:127]
	v_rcp_f32_e32 v196, v196
	v_rcp_f32_e32 v197, v197
	v_pk_mul_f32 v[118:119], v[118:119], s[36:37] op_sel_hi:[1,0]
	v_pk_fma_f32 v[200:201], v[194:195], s[24:25], v[180:181] op_sel_hi:[1,0,0]
	v_pk_mul_f32 v[116:117], v[128:129], v[128:129]
	v_exp_f32_e32 v118, v118
	v_exp_f32_e32 v119, v119
	v_pk_fma_f32 v[200:201], v[194:195], v[200:201], s[28:29] op_sel_hi:[1,1,0]
	v_and_b32_e32 v193, 0x7fffffff, v123
	v_and_b32_e32 v192, 0x7fffffff, v122
	v_pk_mul_f32 v[116:117], v[116:117], s[36:37] op_sel_hi:[1,0]
	v_pk_fma_f32 v[202:203], v[196:197], s[24:25], v[180:181] op_sel_hi:[1,0,0]
	v_pk_fma_f32 v[200:201], v[194:195], v[200:201], s[30:31] op_sel_hi:[1,1,0]
	v_pk_fma_f32 v[198:199], v[192:193], s[22:23], 1.0 op_sel_hi:[1,0,0]
	v_exp_f32_e32 v116, v116
	v_exp_f32_e32 v117, v117
	v_pk_fma_f32 v[202:203], v[196:197], v[202:203], s[28:29] op_sel_hi:[1,1,0]
	v_pk_fma_f32 v[200:201], v[194:195], v[200:201], s[34:35] op_sel_hi:[1,1,0]
	v_rcp_f32_e32 v198, v198
	v_rcp_f32_e32 v199, v199
	v_pk_fma_f32 v[202:203], v[196:197], v[202:203], s[30:31] op_sel_hi:[1,1,0]
	v_pk_mul_f32 v[194:195], v[194:195], v[200:201]
	v_pk_fma_f32 v[202:203], v[196:197], v[202:203], s[34:35] op_sel_hi:[1,1,0]
	v_pk_fma_f32 v[118:119], v[118:119], v[194:195], 0.5 op_sel_hi:[1,1,0] neg_lo:[1,0,0] neg_hi:[1,0,0]
	v_pk_mul_f32 v[196:197], v[196:197], v[202:203]
	v_pk_mul_f32 v[114:115], v[114:115], v[118:119]
	v_pk_fma_f32 v[116:117], v[116:117], v[196:197], 0.5 op_sel_hi:[1,1,0] neg_lo:[1,0,0] neg_hi:[1,0,0]
	v_pk_fma_f32 v[114:115], v[126:127], 0.5, v[114:115] op_sel_hi:[1,0,1]
	v_pk_mul_f32 v[126:127], v[122:123], v[122:123]
	v_pk_mul_f32 v[116:117], v[120:121], v[116:117]
	v_pk_fma_f32 v[118:119], v[198:199], s[24:25], v[180:181] op_sel_hi:[1,0,0]
	v_pk_mul_f32 v[126:127], v[126:127], s[36:37] op_sel_hi:[1,0]
	v_pk_fma_f32 v[116:117], v[128:129], 0.5, v[116:117] op_sel_hi:[1,0,1]
	v_pk_fma_f32 v[118:119], v[198:199], v[118:119], s[28:29] op_sel_hi:[1,1,0]
	v_exp_f32_e32 v126, v126
	v_exp_f32_e32 v127, v127
	v_and_b32_e32 v129, 0x7fffffff, v125
	v_and_b32_e32 v128, 0x7fffffff, v124
	v_pk_fma_f32 v[118:119], v[198:199], v[118:119], s[30:31] op_sel_hi:[1,1,0]
	v_pk_fma_f32 v[194:195], v[128:129], s[22:23], 1.0 op_sel_hi:[1,0,0]
	v_pk_fma_f32 v[118:119], v[198:199], v[118:119], s[34:35] op_sel_hi:[1,1,0]
	v_rcp_f32_e32 v194, v194
	v_rcp_f32_e32 v195, v195
	v_pk_mul_f32 v[118:119], v[198:199], v[118:119]
	v_pk_mul_f32 v[120:121], v[124:125], v[124:125]
	v_pk_fma_f32 v[118:119], v[126:127], v[118:119], 0.5 op_sel_hi:[1,1,0] neg_lo:[1,0,0] neg_hi:[1,0,0]
	v_pk_mul_f32 v[120:121], v[120:121], s[36:37] op_sel_hi:[1,0]
	v_pk_mul_f32 v[118:119], v[192:193], v[118:119]
	v_exp_f32_e32 v120, v120
	v_pk_fma_f32 v[118:119], v[122:123], 0.5, v[118:119] op_sel_hi:[1,0,1]
	v_pk_fma_f32 v[122:123], v[194:195], s[24:25], v[180:181] op_sel_hi:[1,0,0]
	v_exp_f32_e32 v121, v121
	v_pk_fma_f32 v[122:123], v[194:195], v[122:123], s[28:29] op_sel_hi:[1,1,0]
	v_and_b32_e32 v127, 0x7fffffff, v189
	v_pk_fma_f32 v[122:123], v[194:195], v[122:123], s[30:31] op_sel_hi:[1,1,0]
	v_and_b32_e32 v126, 0x7fffffff, v188
	v_pk_fma_f32 v[122:123], v[194:195], v[122:123], s[34:35] op_sel_hi:[1,1,0]
	v_and_b32_e32 v193, 0x7fffffff, v187
	v_pk_mul_f32 v[122:123], v[194:195], v[122:123]
	v_and_b32_e32 v192, 0x7fffffff, v186
	v_pk_fma_f32 v[120:121], v[120:121], v[122:123], 0.5 op_sel_hi:[1,1,0] neg_lo:[1,0,0] neg_hi:[1,0,0]
	v_cvt_pk_bf16_f32 v122, v114, v115
	v_cvt_pk_bf16_f32 v123, v116, v117
	v_pk_fma_f32 v[194:195], v[192:193], s[22:23], 1.0 op_sel_hi:[1,0,0]
	v_pk_mul_f32 v[120:121], v[128:129], v[120:121]
	v_rcp_f32_e32 v194, v194
	v_pk_fma_f32 v[120:121], v[124:125], 0.5, v[120:121] op_sel_hi:[1,0,1]
	v_pk_fma_f32 v[124:125], v[126:127], s[22:23], 1.0 op_sel_hi:[1,0,0]
	v_rcp_f32_e32 v195, v195
	v_rcp_f32_e32 v128, v124
	v_rcp_f32_e32 v129, v125
	v_cvt_pk_bf16_f32 v124, v118, v119
	v_cvt_pk_bf16_f32 v125, v120, v121
	global_store_dwordx4 v[182:183], v[122:125], off
	s_nop 1
	v_pk_fma_f32 v[122:123], v[128:129], s[24:25], v[180:181] op_sel_hi:[1,0,0]
	v_pk_mul_f32 v[124:125], v[186:187], v[186:187]
	v_pk_fma_f32 v[122:123], v[128:129], v[122:123], s[28:29] op_sel_hi:[1,1,0]
	v_pk_mul_f32 v[124:125], v[124:125], s[36:37] op_sel_hi:[1,0]
	v_pk_fma_f32 v[122:123], v[128:129], v[122:123], s[30:31] op_sel_hi:[1,1,0]
	v_exp_f32_e32 v124, v124
	v_pk_fma_f32 v[122:123], v[128:129], v[122:123], s[34:35] op_sel_hi:[1,1,0]
	v_exp_f32_e32 v125, v125
	v_pk_mul_f32 v[122:123], v[128:129], v[122:123]
	v_pk_mul_f32 v[128:129], v[188:189], v[188:189]
	s_nop 0
	v_pk_mul_f32 v[128:129], v[128:129], s[36:37] op_sel_hi:[1,0]
	s_nop 0
	v_exp_f32_e32 v128, v128
	v_exp_f32_e32 v129, v129
	s_nop 0
	v_pk_fma_f32 v[122:123], v[128:129], v[122:123], 0.5 op_sel_hi:[1,1,0] neg_lo:[1,0,0] neg_hi:[1,0,0]
	s_nop 0
	v_pk_mul_f32 v[122:123], v[126:127], v[122:123]
	v_and_b32_e32 v129, 0x7fffffff, v185
	v_and_b32_e32 v128, 0x7fffffff, v184
	v_pk_fma_f32 v[122:123], v[188:189], 0.5, v[122:123] op_sel_hi:[1,0,1]
	v_pk_fma_f32 v[126:127], v[194:195], s[24:25], v[180:181] op_sel_hi:[1,0,0]
	v_pk_fma_f32 v[188:189], v[128:129], s[22:23], 1.0 op_sel_hi:[1,0,0]
	v_pk_fma_f32 v[126:127], v[194:195], v[126:127], s[28:29] op_sel_hi:[1,1,0]
	v_rcp_f32_e32 v188, v188
	v_rcp_f32_e32 v189, v189
	v_pk_fma_f32 v[126:127], v[194:195], v[126:127], s[30:31] op_sel_hi:[1,1,0]
	s_nop 0
	v_pk_fma_f32 v[126:127], v[194:195], v[126:127], s[34:35] op_sel_hi:[1,1,0]
	s_nop 0
	v_pk_mul_f32 v[126:127], v[194:195], v[126:127]
	s_nop 0
	v_pk_fma_f32 v[124:125], v[124:125], v[126:127], 0.5 op_sel_hi:[1,1,0] neg_lo:[1,0,0] neg_hi:[1,0,0]
	v_pk_fma_f32 v[126:127], v[188:189], s[24:25], v[180:181] op_sel_hi:[1,0,0]
	v_pk_mul_f32 v[124:125], v[192:193], v[124:125]
	v_pk_fma_f32 v[126:127], v[188:189], v[126:127], s[28:29] op_sel_hi:[1,1,0]
	v_and_b32_e32 v193, 0x7fffffff, v191
	v_pk_fma_f32 v[126:127], v[188:189], v[126:127], s[30:31] op_sel_hi:[1,1,0]
	v_and_b32_e32 v192, 0x7fffffff, v190
	v_pk_fma_f32 v[126:127], v[188:189], v[126:127], s[34:35] op_sel_hi:[1,1,0]
	v_pk_fma_f32 v[194:195], v[192:193], s[22:23], 1.0 op_sel_hi:[1,0,0]
	v_pk_mul_f32 v[126:127], v[188:189], v[126:127]
	v_pk_mul_f32 v[188:189], v[184:185], v[184:185]
	v_rcp_f32_e32 v194, v194
	v_pk_mul_f32 v[188:189], v[188:189], s[36:37] op_sel_hi:[1,0]
	v_rcp_f32_e32 v195, v195
	v_exp_f32_e32 v188, v188
	v_exp_f32_e32 v189, v189
	v_pk_fma_f32 v[124:125], v[186:187], 0.5, v[124:125] op_sel_hi:[1,0,1]
	v_pk_mul_f32 v[186:187], v[190:191], v[190:191]
	v_pk_fma_f32 v[126:127], v[188:189], v[126:127], 0.5 op_sel_hi:[1,1,0] neg_lo:[1,0,0] neg_hi:[1,0,0]
	s_nop 0
	v_pk_mul_f32 v[126:127], v[128:129], v[126:127]
	v_pk_fma_f32 v[128:129], v[194:195], s[24:25], v[180:181] op_sel_hi:[1,0,0]
	v_pk_mul_f32 v[180:181], v[186:187], s[36:37] op_sel_hi:[1,0]
	v_pk_fma_f32 v[128:129], v[194:195], v[128:129], s[28:29] op_sel_hi:[1,1,0]
	v_exp_f32_e32 v180, v180
	v_exp_f32_e32 v181, v181
	v_pk_fma_f32 v[128:129], v[194:195], v[128:129], s[30:31] op_sel_hi:[1,1,0]
	v_pk_fma_f32 v[126:127], v[184:185], 0.5, v[126:127] op_sel_hi:[1,0,1]
	v_pk_fma_f32 v[128:129], v[194:195], v[128:129], s[34:35] op_sel_hi:[1,1,0]
	v_cvt_pk_bf16_f32 v184, v122, v123
	v_cvt_pk_bf16_f32 v185, v124, v125
	v_cvt_pk_bf16_f32 v186, v126, v127
	s_nop 0
	v_pk_mul_f32 v[128:129], v[194:195], v[128:129]
	s_nop 0
	v_pk_fma_f32 v[128:129], v[180:181], v[128:129], 0.5 op_sel_hi:[1,1,0] neg_lo:[1,0,0] neg_hi:[1,0,0]
	s_nop 0
	v_pk_mul_f32 v[128:129], v[192:193], v[128:129]
	s_nop 0
	v_pk_fma_f32 v[128:129], v[190:191], 0.5, v[128:129] op_sel_hi:[1,0,1]
	s_nop 0
	v_cvt_pk_bf16_f32 v187, v128, v129
	global_store_dwordx4 v[182:183], v[184:187], off offset:256
	s_cbranch_scc1 .LBB0_453
	v_mov_b32_e32 v194, v127
	v_mov_b32_e32 v195, v129
	v_mov_b32_e32 v192, v126
	v_mov_b32_e32 v193, v128
	v_pk_mul_f32 v[194:195], v[194:195], v[194:195]
	v_pk_mul_f32 v[182:183], v[116:117], v[116:117]
	v_pk_fma_f32 v[192:193], v[192:193], v[192:193], v[194:195]
	v_pk_add_f32 v[116:117], v[116:117], v[116:117] op_sel:[0,1] op_sel_hi:[1,0]
	v_pk_mul_f32 v[180:181], v[114:115], v[114:115]
	v_pk_add_f32 v[192:193], v[192:193], v[192:193] op_sel_hi:[0,1]
	v_pk_add_f32 v[114:115], v[114:115], v[114:115] op_sel:[0,1] op_sel_hi:[1,0]
	v_and_b32_e32 v117, 64, v179
	v_xor_b32_e32 v115, 16, v179
	v_add_u32_e32 v192, 64, v117
	v_cmp_lt_i32_e32 vcc, v115, v192
	v_pk_mul_f32 v[184:185], v[118:119], v[118:119]
	v_pk_mul_f32 v[186:187], v[120:121], v[120:121]
	v_pk_mul_f32 v[188:189], v[122:123], v[122:123]
	v_pk_mul_f32 v[190:191], v[124:125], v[124:125]
	v_pk_add_f32 v[118:119], v[118:119], v[118:119] op_sel:[0,1] op_sel_hi:[1,0]
	v_pk_add_f32 v[120:121], v[120:121], v[120:121] op_sel:[0,1] op_sel_hi:[1,0]
	v_cndmask_b32_e32 v115, v179, v115, vcc
	v_lshlrev_b32_e32 v194, 2, v115
	v_mov_b32_e32 v115, v188
	v_mov_b32_e32 v117, v189
	v_mov_b32_e32 v119, v190
	v_mov_b32_e32 v121, v191
	v_pk_add_f32 v[114:115], v[114:115], v[116:117]
	v_pk_add_f32 v[116:117], v[118:119], v[120:121]
	v_mov_b32_e32 v118, v124
	v_pk_add_f32 v[114:115], v[114:115], v[116:117]
	v_mov_b32_e32 v116, v122
	v_mov_b32_e32 v117, v180
	v_mov_b32_e32 v180, v123
	v_mov_b32_e32 v119, v182
	v_mov_b32_e32 v182, v125
	v_pk_add_f32 v[116:117], v[116:117], v[180:181]
	v_pk_add_f32 v[118:119], v[118:119], v[182:183]
	v_mov_b32_e32 v120, v128
	v_pk_add_f32 v[116:117], v[116:117], v[118:119]
	v_mov_b32_e32 v118, v126
	v_mov_b32_e32 v119, v184
	v_mov_b32_e32 v184, v127
	v_mov_b32_e32 v121, v186
	v_mov_b32_e32 v186, v129
	v_pk_add_f32 v[118:119], v[118:119], v[184:185]
	v_pk_add_f32 v[120:121], v[120:121], v[186:187]
	v_mov_b32_e32 v139, v193
	v_pk_add_f32 v[118:119], v[118:119], v[120:121]
	v_pk_add_f32 v[114:115], v[114:115], v[138:139]
	v_pk_add_f32 v[116:117], v[116:117], v[118:119]
	v_xor_b32_e32 v118, 32, v179
	v_pk_add_f32 v[114:115], v[116:117], v[114:115]
	ds_bpermute_b32 v116, v194, v114
	ds_bpermute_b32 v117, v194, v115
	v_cmp_lt_i32_e32 vcc, v118, v192
	s_waitcnt lgkmcnt(0)
	v_pk_add_f32 v[114:115], v[114:115], v[116:117]
	v_cndmask_b32_e32 v118, v179, v118, vcc
	v_lshlrev_b32_e32 v118, 2, v118
	ds_bpermute_b32 v116, v118, v114
	ds_bpermute_b32 v117, v118, v115
	s_and_saveexec_b64 s[4:5], s[2:3]
	s_cbranch_execz .LBB0_452
	s_lshl_b32 s8, s6, 2
	s_waitcnt lgkmcnt(0)
	v_pk_add_f32 v[114:115], v[114:115], v[116:117]
	v_lshlrev_b64 v[116:117], 6, v[176:177]
	s_sub_i32 s8, s8, 64
	v_lshl_add_u64 v[116:117], v[116:117], 0, s[8:9]
	v_or_b32_e32 v116, s54, v116
	v_lshl_add_u64 v[116:117], v[116:117], 3, s[12:13]
	global_store_dwordx2 v[116:117], v[114:115], off
